# non-temporal hint on read-once streams: sample-attention KV-cache tile loads, prologue x loads, HGRN per-step input loads
# speedup vs baseline: 1.0140x; 1.0047x over previous
.LBB0_88:
	s_add_i32 s4, s14, 0xffff0000
	s_ashr_i32 s15, s14, 31
	s_cmp_lt_i32 s14, 0x10000
	s_cselect_b32 s6, 0, 8
	s_cselect_b32 s5, s15, 0
	s_cselect_b32 s4, s14, s4
	s_add_u32 s6, s0, s6
	s_addc_u32 s7, s1, 0
	s_load_dwordx2 s[6:7], s[6:7], 0x0
	s_lshl_b64 s[4:5], s[4:5], 12
	s_waitcnt lgkmcnt(0)
	s_add_u32 s4, s6, s4
	s_addc_u32 s5, s7, s5
	v_lshl_add_u64 v[72:73], v[68:69], 2, s[4:5]
	global_load_dwordx4 v[62:65], v[72:73], off nt
	global_load_dwordx4 v[58:61], v[72:73], off offset:16 nt
	global_load_dwordx4 v[54:57], v[72:73], off offset:2048 nt
	global_load_dwordx4 v[50:53], v[72:73], off offset:2064 nt
	s_add_i32 s4, s14, s27
	s_cmp_lt_i32 s4, 0x10200
	s_cselect_b64 s[6:7], -1, 0
	s_cmp_gt_i32 s4, 0x101ff
	s_cbranch_scc1 .LBB0_90
	s_ashr_i32 s5, s4, 31
	s_add_i32 s8, s4, 0xffff0000
	s_cmp_lt_i32 s4, 0x10000
	s_cselect_b32 s9, s5, 0
	s_cselect_b32 s5, 0, 8
	s_cselect_b32 s8, s4, s8
	s_add_u32 s10, s0, s5
	s_addc_u32 s11, s1, 0
	s_load_dwordx2 s[10:11], s[10:11], 0x0
	s_lshl_b64 s[8:9], s[8:9], 12
	s_waitcnt lgkmcnt(0)
	s_add_u32 s8, s10, s8
	s_addc_u32 s9, s11, s9
	v_lshl_add_u64 v[72:73], v[68:69], 2, s[8:9]
	global_load_dwordx4 v[46:49], v[72:73], off nt
	global_load_dwordx4 v[42:45], v[72:73], off offset:16 nt
	global_load_dwordx4 v[38:41], v[72:73], off offset:2048 nt
	global_load_dwordx4 v[34:37], v[72:73], off offset:2064 nt
.LBB0_90:
	s_add_i32 s8, s20, s14
	s_cmp_lt_i32 s8, 0x10200
	s_cselect_b64 s[10:11], -1, 0
	s_cmp_gt_i32 s8, 0x101ff
	s_cbranch_scc1 .LBB0_92
	s_ashr_i32 s5, s8, 31
	s_add_i32 s9, s8, 0xffff0000
	s_cmp_lt_i32 s8, 0x10000
	s_cselect_b32 s17, s5, 0
	s_cselect_b32 s5, 0, 8
	s_cselect_b32 s16, s8, s9
	s_add_u32 s18, s0, s5
	s_addc_u32 s19, s1, 0
	s_load_dwordx2 s[18:19], s[18:19], 0x0
	s_lshl_b64 s[16:17], s[16:17], 12
	s_waitcnt lgkmcnt(0)
	s_add_u32 s16, s18, s16
	s_addc_u32 s17, s19, s17
	v_lshl_add_u64 v[72:73], v[68:69], 2, s[16:17]
	global_load_dwordx4 v[30:33], v[72:73], off nt
	global_load_dwordx4 v[26:29], v[72:73], off offset:16 nt
	global_load_dwordx4 v[22:25], v[72:73], off offset:2048 nt
	global_load_dwordx4 v[18:21], v[72:73], off offset:2064 nt
.LBB0_92:
	s_add_i32 s16, s21, s14
	s_cmp_lt_i32 s16, 0x10200
	s_cselect_b64 s[18:19], -1, 0
	s_cmp_gt_i32 s16, 0x101ff
	s_cbranch_scc1 .LBB0_94
	s_ashr_i32 s5, s16, 31
	s_add_i32 s9, s16, 0xffff0000
	s_cmp_lt_i32 s16, 0x10000
	s_cselect_b32 s23, s5, 0
	s_cselect_b32 s5, 0, 8
	s_cselect_b32 s22, s16, s9
	s_add_u32 s24, s0, s5
	s_addc_u32 s25, s1, 0
	s_load_dwordx2 s[24:25], s[24:25], 0x0
	s_lshl_b64 s[22:23], s[22:23], 12
	s_waitcnt lgkmcnt(0)
	s_add_u32 s22, s24, s22
	s_addc_u32 s23, s25, s23
	v_lshl_add_u64 v[72:73], v[68:69], 2, s[22:23]
	global_load_dwordx4 v[14:17], v[72:73], off nt
	global_load_dwordx4 v[10:13], v[72:73], off offset:16 nt
	global_load_dwordx4 v[6:9], v[72:73], off offset:2048 nt
	global_load_dwordx4 v[2:5], v[72:73], off offset:2064 nt

.LBB0_983:
	v_mov_b32_e32 v6, v228
	s_ashr_i32 s88, s85, 2
	s_and_b32 s86, s85, 3
	s_ashr_i32 s89, s88, 31
	v_readfirstlane_b32 s44, v6
	s_bfe_u32 s36, s44, 0x20006
	s_lshl_b32 s92, s86, 9
	s_add_u32 s42, s7, s92
	v_ashrrev_i32_e32 v80, 4, v6
	s_addc_u32 s43, s84, 0
	s_lshl_b64 s[90:91], s[88:89], 11
	v_ashrrev_i32_e32 v81, 31, v80
	v_lshl_add_u64 v[2:3], s[90:91], 0, v[80:81]
	v_lshlrev_b32_e32 v0, 3, v6
	v_lshlrev_b64 v[4:5], 11, v[2:3]
	v_and_b32_e32 v0, 0x78, v0
	v_lshl_add_u64 v[4:5], s[82:83], 0, v[4:5]
	v_lshl_add_u64 v[4:5], v[4:5], 0, s[92:93]
	v_lshlrev_b32_e32 v160, 2, v0
	v_lshl_add_u64 v[4:5], v[4:5], 0, v[160:161]
	global_load_dwordx4 v[44:47], v[4:5], off offset:16 nt
	global_load_dwordx4 v[32:35], v[4:5], off nt
	v_mov_b64_e32 v[4:5], s[4:5]
	v_mad_u64_u32 v[4:5], s[22:23], v2, s3, v[4:5]
	v_mad_i32_i24 v5, v3, s3, v5
	s_lshl_b32 s76, s86, 8
	s_mov_b32 s77, s93
	v_lshl_add_u64 v[2:3], v[4:5], 0, s[76:77]
	v_lshlrev_b32_e32 v82, 1, v0
	v_mov_b32_e32 v83, v161
	v_lshl_add_u64 v[2:3], v[2:3], 0, v[82:83]
	global_load_dwordx4 v[40:43], v[2:3], off nt
	global_load_dwordx4 v[36:39], v[2:3], off offset:2048 nt
	global_load_dwordx4 v[68:71], v[2:3], off offset:3072 nt
	v_and_b32_e32 v1, 0x7f, v6
	v_lshlrev_b32_e32 v2, 5, v6
	s_ashr_i32 s19, s44, 8
	v_and_b32_e32 v2, 0xfffff000, v2
	v_lshlrev_b32_e32 v1, 2, v1
	s_movk_i32 s2, 0x110
	s_add_u32 s22, s82, s92
	v_add3_u32 v100, 0, v2, v1
	v_mul_lo_u32 v1, v80, s2
	v_and_b32_e32 v87, 63, v6
	s_addc_u32 s23, s83, 0
	v_add_u32_e32 v86, 0, v1
	v_and_b32_e32 v7, 31, v6
	v_lshl_add_u64 v[84:85], s[22:23], 0, v[160:161]
	v_mad_u64_u32 v[2:3], s[22:23], v80, 48, v[86:87]
	s_cmp_lt_u32 s44, 64
	s_cselect_b64 s[22:23], -1, 0
	v_mad_u32_u24 v104, v7, s2, 0
	v_and_b32_e32 v10, 3, v6
	v_bfe_u32 v11, v6, 4, 1
	s_cmpk_lt_u32 s44, 0x100
	v_lshl_or_b32 v1, s19, 5, v7
	s_movk_i32 s45, 0x210
	v_bfe_u32 v8, v6, 5, 1
	v_lshl_add_u32 v5, s19, 7, v104
	s_cselect_b64 s[24:25], -1, 0
	s_lshl_b32 s37, s36, 7
	v_mul_lo_u32 v12, v1, s45
	s_lshl_b32 s19, s19, 6
	v_lshlrev_b32_e32 v1, 4, v11
	v_lshlrev_b32_e32 v14, 2, v10
	s_lshl_b32 s92, s36, 5
	v_lshlrev_b32_e32 v105, 4, v8
	s_add_i32 s37, s37, 0
	v_or3_b32 v15, s19, v1, v14
	v_or3_b32 v1, v1, s92, v14
	s_and_b32 s36, s44, 0xffffff00
	s_movk_i32 s2, 0x84
	v_add_u32_e32 v13, s37, v105
	v_lshl_add_u32 v14, v1, 1, 0
	s_add_i32 s81, s36, 0
	v_mad_u64_u32 v[0:1], s[36:37], v80, s2, v[0:1]
	s_add_u32 s36, s75, s76
	s_addc_u32 s37, s6, 0
	v_lshlrev_b32_e32 v3, 3, v8
	v_lshl_add_u64 v[88:89], s[36:37], 0, v[82:83]
	v_lshlrev_b32_e32 v8, 2, v8
	s_and_b32 s36, s44, 0xc0
	v_lshlrev_b32_e32 v11, 5, v11
	v_lshlrev_b32_e32 v10, 3, v10
	v_or3_b32 v10, v11, s36, v10
	v_or_b32_e32 v11, 2, v8
	v_cmp_gt_u32_e64 s[46:47], v11, v7
	v_or_b32_e32 v11, 3, v8
	v_cmp_gt_u32_e64 s[48:49], v11, v7
	v_or_b32_e32 v11, 8, v8
	v_cmp_gt_u32_e64 s[50:51], v11, v7
	v_or_b32_e32 v11, 9, v8
	v_cmp_gt_u32_e64 s[52:53], v11, v7
	v_or_b32_e32 v11, 10, v8
	v_cmp_gt_u32_e64 s[54:55], v11, v7
	v_or_b32_e32 v11, 11, v8
	v_cmp_gt_u32_e64 s[56:57], v11, v7
	v_or_b32_e32 v11, 16, v8
	v_cmp_gt_u32_e64 s[58:59], v11, v7
	v_or_b32_e32 v11, 17, v8
	v_cmp_gt_u32_e64 s[60:61], v11, v7
	v_or_b32_e32 v11, 18, v8
	v_cmp_gt_u32_e64 s[62:63], v11, v7
	v_or_b32_e32 v11, 19, v8
	v_cmp_gt_u32_e64 s[64:65], v11, v7
	v_or_b32_e32 v11, 24, v8
	v_cmp_gt_u32_e64 s[66:67], v11, v7
	v_or_b32_e32 v11, 25, v8
	v_cmp_gt_u32_e64 s[68:69], v11, v7
	v_or_b32_e32 v11, 26, v8
	v_bfe_u32 v9, v6, 2, 2
	v_cmp_gt_u32_e64 s[70:71], v11, v7
	v_or_b32_e32 v11, 27, v8
	s_add_u32 s36, s4, s76
	v_mad_u32_u24 v1, v7, 48, v104
	v_lshl_add_u64 v[90:91], s[42:43], 0, v[160:161]
	v_cmp_gt_u32_e64 s[42:43], v8, v7
	v_cmp_lt_u32_e64 s[44:45], v8, v7
	v_cmp_gt_u32_e64 s[72:73], v11, v7
	v_or_b32_e32 v7, v8, v9
	s_movk_i32 s2, 0x140
	v_or_b32_e32 v8, v3, v9
	s_addc_u32 s37, s5, 0
	v_lshl_add_u32 v4, v80, 9, 0
	v_ashrrev_i32_e32 v102, 7, v6
	v_lshlrev_b32_e32 v16, 4, v87
	v_mad_u32_u24 v7, v7, s2, 0
	v_mul_u32_u24_e32 v8, 0x140, v8
	v_lshl_add_u32 v9, v15, 1, 0
	v_lshl_add_u32 v106, v0, 2, 0
	v_lshl_add_u64 v[92:93], s[36:37], 0, v[82:83]
	v_and_b32_e32 v0, 15, v6
	s_add_i32 s36, 0, 0x4000
	v_mov_b32_e32 v96, 0
	s_waitcnt vmcnt(0)
	v_mov_b64_e32 v[56:57], v[68:69]
	v_mov_b64_e32 v[62:63], v[38:39]
	v_mov_b64_e32 v[66:67], v[42:43]
	v_mov_b64_e32 v[50:51], v[46:47]
	v_mov_b64_e32 v[54:55], v[34:35]
	v_lshl_add_u32 v101, v6, 2, 0
	s_mov_b32 s87, 0
	v_cmp_lt_i32_e64 s[38:39], 0, v102
	v_cmp_eq_u32_e64 s[40:41], 31, v80
	v_add_u32_e32 v103, 0, v160
	v_add_u32_e32 v107, 0xc400, v106
	v_lshl_add_u32 v83, v0, 5, s36
	v_add_u32_e32 v108, v2, v82
	v_add_u32_e32 v109, v1, v105
	v_add_u32_e32 v110, v5, v3
	v_add_u32_e32 v111, v7, v10
	v_add_u32_e32 v112, v13, v12
	v_add_u32_e32 v113, v9, v8
	v_add_u32_e32 v114, v14, v8
	v_add_u32_e32 v115, v4, v160
	v_add_u32_e32 v116, 0, v16
	v_mov_b32_e32 v97, v96
	v_mov_b32_e32 v16, v96
	v_mov_b32_e32 v17, v96
	v_mov_b32_e32 v18, v96
	v_mov_b32_e32 v19, v96
	v_mov_b32_e32 v20, v96
	v_mov_b32_e32 v21, v96
	v_mov_b32_e32 v22, v96
	v_mov_b32_e32 v23, v96
	v_mov_b32_e32 v24, v96
	v_mov_b32_e32 v25, v96
	v_mov_b32_e32 v26, v96
	v_mov_b32_e32 v27, v96
	v_mov_b32_e32 v28, v96
	v_mov_b32_e32 v29, v96
	v_mov_b32_e32 v30, v96
	v_mov_b32_e32 v31, v96
	v_mov_b32_e32 v98, v96
	v_mov_b32_e32 v99, v96
	v_mov_b32_e32 v0, v96
	v_mov_b32_e32 v1, v96
	v_mov_b32_e32 v2, v96
	v_mov_b32_e32 v3, v96
	v_mov_b32_e32 v4, v96
	v_mov_b32_e32 v5, v96
	v_mov_b32_e32 v6, v96
	v_mov_b32_e32 v7, v96
	v_mov_b32_e32 v8, v96
	v_mov_b32_e32 v9, v96
	v_mov_b32_e32 v10, v96
	v_mov_b32_e32 v11, v96
	v_mov_b32_e32 v12, v96
	v_mov_b32_e32 v13, v96
	v_mov_b32_e32 v14, v96
	v_mov_b32_e32 v15, v96
	v_mov_b64_e32 v[58:59], v[70:71]
	v_mov_b64_e32 v[60:61], v[36:37]
	v_mov_b64_e32 v[64:65], v[40:41]
	v_mov_b64_e32 v[48:49], v[44:45]
	v_mov_b64_e32 v[52:53], v[32:33]
	s_branch .LBB0_985

.LBB0_985:
	s_lshl_b32 s36, s87, 5
	s_or_b32 s36, s90, s36
	s_mov_b32 s37, s91
	v_lshl_add_u64 v[94:95], s[36:37], 0, v[80:81]
	s_cmp_eq_u32 s87, 63
	ds_write_b128 v115, v[32:35]
	ds_write_b128 v115, v[44:47] offset:16
	s_cbranch_scc1 .LBB0_987
	v_lshl_add_u64 v[56:57], v[94:95], 0, 32
	v_mad_u64_u32 v[58:59], s[36:37], v56, s3, v[92:93]
	v_lshlrev_b64 v[48:49], 11, v[56:57]
	v_mov_b32_e32 v56, v59
	v_mad_u64_u32 v[56:57], s[36:37], v57, s3, v[56:57]
	v_lshl_add_u64 v[52:53], v[84:85], 0, v[48:49]
	v_mov_b32_e32 v59, v56
	global_load_dwordx4 v[48:51], v[52:53], off offset:16 nt
	s_nop 0
	global_load_dwordx4 v[52:55], v[52:53], off nt
	s_nop 0
	global_load_dwordx4 v[64:67], v[58:59], off nt
	global_load_dwordx4 v[60:63], v[58:59], off offset:2048 nt
	s_nop 0
	global_load_dwordx4 v[56:59], v[58:59], off offset:3072 nt

.LBB0_1021:
	v_mov_b64_e32 v[72:73], v[166:167]
	v_mov_b64_e32 v[74:75], v[164:165]
	v_mov_b64_e32 v[76:77], v[162:163]
	v_mov_b64_e32 v[78:79], v[158:159]
	s_mov_b32 s6, s55
	s_mov_b32 s7, 0
	s_cmp_lt_u32 s55, 61
	s_cbranch_scc0 .LBB0_1023
	s_lshl_b64 s[4:5], s[26:27], 1
	s_add_u32 s8, s4, s26
	s_addc_u32 s9, s5, s27
	v_lshl_add_u64 v[92:93], v[162:163], 0, v[160:161]
	v_lshl_add_u64 v[94:95], v[158:159], 0, v[160:161]
	global_load_dwordx4 v[64:67], v[92:93], off nt
	global_load_dwordx4 v[68:71], v[92:93], off offset:16 nt
	global_load_dwordx4 v[72:75], v[94:95], off nt
	global_load_dwordx4 v[76:79], v[94:95], off offset:16 nt
	v_lshl_add_u64 v[92:93], v[164:165], 0, v[160:161]
	v_lshl_add_u64 v[94:95], v[166:167], 0, v[160:161]
	global_load_dwordx4 v[80:83], v[92:93], off offset:-16 nt
	global_load_dwordx4 v[84:87], v[92:93], off nt
	global_load_dwordx4 v[88:91], v[94:95], off nt
	global_load_dwordx4 v[92:95], v[94:95], off offset:16 nt
	v_lshl_add_u64 v[124:125], v[162:163], 0, v[160:161]
	v_lshl_add_u64 v[124:125], v[124:125], 0, s[26:27]
	v_lshl_add_u64 v[126:127], v[158:159], 0, v[160:161]
	v_lshl_add_u64 v[126:127], v[126:127], 0, s[26:27]
	global_load_dwordx4 v[96:99], v[124:125], off nt
	global_load_dwordx4 v[100:103], v[124:125], off offset:16 nt
	global_load_dwordx4 v[104:107], v[126:127], off nt
	global_load_dwordx4 v[108:111], v[126:127], off offset:16 nt
	v_lshl_add_u64 v[124:125], v[164:165], 0, v[160:161]
	v_lshl_add_u64 v[124:125], v[124:125], 0, s[26:27]
	v_lshl_add_u64 v[126:127], v[166:167], 0, v[160:161]
	v_lshl_add_u64 v[126:127], v[126:127], 0, s[26:27]
	global_load_dwordx4 v[112:115], v[124:125], off offset:-16 nt
	global_load_dwordx4 v[116:119], v[124:125], off nt
	global_load_dwordx4 v[120:123], v[126:127], off nt
	global_load_dwordx4 v[124:127], v[126:127], off offset:16 nt
	s_waitcnt vmcnt(8)
	v_cvt_pk_bf16_f32 v64, v64, v65
	v_cvt_pk_bf16_f32 v65, v66, v67
	v_cvt_pk_bf16_f32 v66, v68, v69
	v_cvt_pk_bf16_f32 v67, v70, v71
	v_cvt_pk_bf16_f32 v68, v72, v73
	v_cvt_pk_bf16_f32 v69, v74, v75
	v_cvt_pk_bf16_f32 v70, v76, v77
	v_cvt_pk_bf16_f32 v71, v78, v79
	v_cvt_pk_bf16_f32 v72, v80, v81
	v_cvt_pk_bf16_f32 v73, v82, v83
	v_cvt_pk_bf16_f32 v74, v84, v85
	v_cvt_pk_bf16_f32 v75, v86, v87
	v_cvt_pk_bf16_f32 v76, v88, v89
	v_cvt_pk_bf16_f32 v77, v90, v91
	v_cvt_pk_bf16_f32 v78, v92, v93
	v_cvt_pk_bf16_f32 v79, v94, v95
	v_add_u32_e32 v80, 0x0, v212
	v_add_u32_e32 v81, 0x0, v215
	v_add_u32_e32 v82, 0x0, v213
	v_add_u32_e32 v83, 0x0, v214
	ds_write_b128 v80, v[64:67]
	ds_write_b128 v81, v[68:71]
	ds_write_b128 v82, v[72:75]
	ds_write_b128 v83, v[76:79]
	v_lshl_add_u64 v[92:93], v[162:163], 0, v[160:161]
	v_lshl_add_u64 v[92:93], v[92:93], 0, s[4:5]
	v_lshl_add_u64 v[94:95], v[158:159], 0, v[160:161]
	v_lshl_add_u64 v[94:95], v[94:95], 0, s[4:5]
	global_load_dwordx4 v[64:67], v[92:93], off nt
	global_load_dwordx4 v[68:71], v[92:93], off offset:16 nt
	global_load_dwordx4 v[72:75], v[94:95], off nt
	global_load_dwordx4 v[76:79], v[94:95], off offset:16 nt
	v_lshl_add_u64 v[92:93], v[164:165], 0, v[160:161]
	v_lshl_add_u64 v[92:93], v[92:93], 0, s[4:5]
	v_lshl_add_u64 v[94:95], v[166:167], 0, v[160:161]
	v_lshl_add_u64 v[94:95], v[94:95], 0, s[4:5]
	global_load_dwordx4 v[80:83], v[92:93], off offset:-16 nt
	global_load_dwordx4 v[84:87], v[92:93], off nt
	global_load_dwordx4 v[88:91], v[94:95], off nt
	global_load_dwordx4 v[92:95], v[94:95], off offset:16 nt
	s_waitcnt vmcnt(8)
	v_cvt_pk_bf16_f32 v96, v96, v97
	v_cvt_pk_bf16_f32 v97, v98, v99
	v_cvt_pk_bf16_f32 v98, v100, v101
	v_cvt_pk_bf16_f32 v99, v102, v103
	v_cvt_pk_bf16_f32 v100, v104, v105
	v_cvt_pk_bf16_f32 v101, v106, v107
	v_cvt_pk_bf16_f32 v102, v108, v109
	v_cvt_pk_bf16_f32 v103, v110, v111
	v_cvt_pk_bf16_f32 v104, v112, v113
	v_cvt_pk_bf16_f32 v105, v114, v115
	v_cvt_pk_bf16_f32 v106, v116, v117
	v_cvt_pk_bf16_f32 v107, v118, v119
	v_cvt_pk_bf16_f32 v108, v120, v121
	v_cvt_pk_bf16_f32 v109, v122, v123
	v_cvt_pk_bf16_f32 v110, v124, v125
	v_cvt_pk_bf16_f32 v111, v126, v127
	v_add_u32_e32 v112, 0x9400, v212
	v_add_u32_e32 v113, 0x9400, v215
	v_add_u32_e32 v114, 0x9400, v213
	v_add_u32_e32 v115, 0x9400, v214
	ds_write_b128 v112, v[96:99]
	ds_write_b128 v113, v[100:103]
	ds_write_b128 v114, v[104:107]
	ds_write_b128 v115, v[108:111]
	v_lshl_add_u64 v[124:125], v[162:163], 0, v[160:161]
	v_lshl_add_u64 v[124:125], v[124:125], 0, s[8:9]
	v_lshl_add_u64 v[126:127], v[158:159], 0, v[160:161]
	v_lshl_add_u64 v[126:127], v[126:127], 0, s[8:9]
	global_load_dwordx4 v[96:99], v[124:125], off nt
	global_load_dwordx4 v[100:103], v[124:125], off offset:16 nt
	global_load_dwordx4 v[104:107], v[126:127], off nt
	global_load_dwordx4 v[108:111], v[126:127], off offset:16 nt
	v_lshl_add_u64 v[124:125], v[164:165], 0, v[160:161]
	v_lshl_add_u64 v[124:125], v[124:125], 0, s[8:9]
	v_lshl_add_u64 v[126:127], v[166:167], 0, v[160:161]
	v_lshl_add_u64 v[126:127], v[126:127], 0, s[8:9]
	global_load_dwordx4 v[112:115], v[124:125], off offset:-16 nt
	global_load_dwordx4 v[116:119], v[124:125], off nt
	global_load_dwordx4 v[120:123], v[126:127], off nt
	global_load_dwordx4 v[124:127], v[126:127], off offset:16 nt
	s_waitcnt vmcnt(8)
	v_cvt_pk_bf16_f32 v64, v64, v65
	v_cvt_pk_bf16_f32 v65, v66, v67
	v_cvt_pk_bf16_f32 v66, v68, v69
	v_cvt_pk_bf16_f32 v67, v70, v71
	v_cvt_pk_bf16_f32 v68, v72, v73
	v_cvt_pk_bf16_f32 v69, v74, v75
	v_cvt_pk_bf16_f32 v70, v76, v77
	v_cvt_pk_bf16_f32 v71, v78, v79
	v_cvt_pk_bf16_f32 v72, v80, v81
	v_cvt_pk_bf16_f32 v73, v82, v83
	v_cvt_pk_bf16_f32 v74, v84, v85
	v_cvt_pk_bf16_f32 v75, v86, v87
	v_cvt_pk_bf16_f32 v76, v88, v89
	v_cvt_pk_bf16_f32 v77, v90, v91
	v_cvt_pk_bf16_f32 v78, v92, v93
	v_cvt_pk_bf16_f32 v79, v94, v95
	v_add_u32_e32 v80, 0x12800, v212
	v_add_u32_e32 v81, 0x12800, v215
	v_add_u32_e32 v82, 0x12800, v213
	v_add_u32_e32 v83, 0x12800, v214
	ds_write_b128 v80, v[64:67]
	ds_write_b128 v81, v[68:71]
	ds_write_b128 v82, v[72:75]
	ds_write_b128 v83, v[76:79]
	s_waitcnt vmcnt(0)
	v_cvt_pk_bf16_f32 v96, v96, v97
	v_cvt_pk_bf16_f32 v97, v98, v99
	v_cvt_pk_bf16_f32 v98, v100, v101
	v_cvt_pk_bf16_f32 v99, v102, v103
	v_cvt_pk_bf16_f32 v100, v104, v105
	v_cvt_pk_bf16_f32 v101, v106, v107
	v_cvt_pk_bf16_f32 v102, v108, v109
	v_cvt_pk_bf16_f32 v103, v110, v111
	v_cvt_pk_bf16_f32 v104, v112, v113
	v_cvt_pk_bf16_f32 v105, v114, v115
	v_cvt_pk_bf16_f32 v106, v116, v117
	v_cvt_pk_bf16_f32 v107, v118, v119
	v_cvt_pk_bf16_f32 v108, v120, v121
	v_cvt_pk_bf16_f32 v109, v122, v123
	v_cvt_pk_bf16_f32 v110, v124, v125
	v_cvt_pk_bf16_f32 v111, v126, v127
	v_add_u32_e32 v112, 0x1bc00, v212
	v_add_u32_e32 v113, 0x1bc00, v215
	v_add_u32_e32 v114, 0x1bc00, v213
	v_add_u32_e32 v115, 0x1bc00, v214
	ds_write_b128 v112, v[96:99]
	ds_write_b128 v113, v[100:103]
	ds_write_b128 v114, v[104:107]
	ds_write_b128 v115, v[108:111]
	s_branch .LBB0_1035
	s_branch .LBB0_1023

.LBB0_1023:
	s_cmp_gt_u32 s6, 63
	s_cselect_b64 s[8:9], -1, 0
	s_cmp_eq_u32 s57, s7
	s_mov_b64 s[22:23], -1
	s_cselect_b64 s[4:5], -1, 0
	s_and_b64 vcc, exec, s[8:9]
	s_cbranch_vccz .LBB0_1027
	s_and_b64 s[60:61], s[38:39], s[4:5]
	v_mov_b32_e32 v67, 0
	v_mov_b32_e32 v66, 0
	v_mov_b32_e32 v65, 0
	v_mov_b32_e32 v64, 0
	v_mov_b32_e32 v71, 0
	v_mov_b32_e32 v70, 0
	v_mov_b32_e32 v69, 0
	v_mov_b32_e32 v68, 0
	s_and_saveexec_b64 s[22:23], s[60:61]
	s_cbranch_execz .LBB0_1026
	global_load_dwordx4 v[64:67], v[150:151], off nt
	global_load_dwordx4 v[68:71], v[152:153], off nt

.LBB0_1027:
	s_andn2_b64 vcc, exec, s[22:23]
	s_cbranch_vccnz .LBB0_1029
	s_waitcnt vmcnt(0)
	v_lshl_add_u64 v[68:69], v[76:77], 0, v[160:161]
	v_lshl_add_u64 v[84:85], v[78:79], 0, v[160:161]
	global_load_dwordx4 v[64:67], v[68:69], off nt
	s_nop 0
	global_load_dwordx4 v[68:71], v[68:69], off offset:16 nt
	s_nop 0
	global_load_dwordx4 v[80:83], v[84:85], off nt
	s_nop 0
	global_load_dwordx4 v[84:87], v[84:85], off offset:16 nt
	s_waitcnt vmcnt(3)
	v_cvt_pk_bf16_f32 v64, v64, v65
	v_cvt_pk_bf16_f32 v65, v66, v67
	s_waitcnt vmcnt(2)
	v_cvt_pk_bf16_f32 v66, v68, v69
	v_cvt_pk_bf16_f32 v67, v70, v71
	s_waitcnt vmcnt(1)
	v_cvt_pk_bf16_f32 v68, v80, v81
	v_cvt_pk_bf16_f32 v69, v82, v83
	s_waitcnt vmcnt(0)
	v_cvt_pk_bf16_f32 v70, v84, v85
	v_cvt_pk_bf16_f32 v71, v86, v87
.LBB0_1029:
	v_add_u32_e32 v80, s7, v212
	s_waitcnt vmcnt(1)
	ds_write_b128 v80, v[64:67]
	v_add_u32_e32 v64, s7, v215
	s_andn2_b64 vcc, exec, s[8:9]
	s_mov_b64 s[8:9], -1
	s_waitcnt vmcnt(0)
	ds_write_b128 v64, v[68:71]
	s_cbranch_vccnz .LBB0_1033
	s_and_b64 s[8:9], s[4:5], s[40:41]
	v_mov_b32_e32 v67, 0
	v_mov_b32_e32 v66, 0
	v_mov_b32_e32 v65, 0
	v_mov_b32_e32 v64, 0
	v_mov_b32_e32 v71, 0
	v_mov_b32_e32 v70, 0
	v_mov_b32_e32 v69, 0
	v_mov_b32_e32 v68, 0
	s_and_saveexec_b64 s[4:5], s[8:9]
	s_cbranch_execz .LBB0_1032
	global_load_dwordx4 v[64:67], v[154:155], off nt
	global_load_dwordx4 v[68:71], v[156:157], off nt

.LBB0_1033:
	s_andn2_b64 vcc, exec, s[8:9]
	s_cbranch_vccnz .LBB0_1022
	s_waitcnt vmcnt(0)
	v_lshl_add_u64 v[68:69], v[74:75], 0, v[160:161]
	v_lshl_add_u64 v[84:85], v[72:73], 0, v[160:161]
	global_load_dwordx4 v[64:67], v[68:69], off offset:-16 nt
	s_nop 0
	global_load_dwordx4 v[68:71], v[68:69], off nt
	s_nop 0
	global_load_dwordx4 v[80:83], v[84:85], off nt
	s_nop 0
	global_load_dwordx4 v[84:87], v[84:85], off offset:16 nt
	s_waitcnt vmcnt(3)
	v_cvt_pk_bf16_f32 v64, v64, v65
	v_cvt_pk_bf16_f32 v65, v66, v67
	s_waitcnt vmcnt(2)
	v_cvt_pk_bf16_f32 v66, v68, v69
	v_cvt_pk_bf16_f32 v67, v70, v71
	s_waitcnt vmcnt(1)
	v_cvt_pk_bf16_f32 v68, v80, v81
	v_cvt_pk_bf16_f32 v69, v82, v83
	s_waitcnt vmcnt(0)
	v_cvt_pk_bf16_f32 v70, v84, v85
	v_cvt_pk_bf16_f32 v71, v86, v87
	s_branch .LBB0_1022
